# MLA phase start: the 16 per-XCC counter reads issued together instead of 16 serial round trips (stagger reverted)
# speedup vs baseline: 1.0002x; 1.0002x over previous
; DI unsigned xb_ld(unsigned* p)              { return __hip_atomic_load(p, __ATOMIC_RELAXED, __HIP_MEMORY_SCOPE_AGENT); }
; DI unsigned xb_add(unsigned* p, unsigned v) { return __hip_atomic_fetch_add(p, v, __ATOMIC_RELAXED, __HIP_MEMORY_SCOPE_AGENT); }
; DI unsigned xb_xcc_id() { return (unsigned)__builtin_amdgcn_s_getreg((3 << 11) | 20) & 0xFu; }
; __global__ void __launch_bounds__(512, 2) hymba_fwd(Params p_unused) {
;     ...
;           if (threadIdx.x == 0) {
;               unsigned* ctl = (unsigned*)(ws + WS_CTL); int pr0 = -1;
;               if (gridDim.x == 256) { bool uni = true;
;                   for (int jx = 0; jx < 16; ++jx) uni = uni && (xb_ld(&ctl[XB_XCNT(jx)]) == (jx < 8 ? 32u : 0u));
;                   if (uni) { const unsigned xcc = xb_xcc_id(); const unsigned tkt = xb_add(&ctl[8192 + l * 16 + xcc], 1u); if (xcc < 8 && tkt < 32) pr0 = (int)((xcc * 4 + (tkt >> 3)) * 8 + (tkt & 7)); } }
;               *tk = pr0;
.LBB0_1021:
	v_readlane_b32 s0, v253, 3
	v_readlane_b32 s1, v253, 4
	s_barrier
	s_load_dwordx2 s[6:7], s[0:1], 0xd8
	s_mov_b64 s[8:9], exec
	v_readlane_b32 s0, v253, 0
	v_readlane_b32 s1, v253, 1
	s_and_b64 s[0:1], s[8:9], s[0:1]
	s_mov_b64 exec, s[0:1]
	s_cbranch_execz .LBB0_1044
	v_readlane_b32 s0, v253, 57
	v_readlane_b32 s1, v253, 58
	v_mov_b32_e32 v0, -1
	s_andn2_b64 vcc, exec, s[0:1]
	s_cbranch_vccnz .LBB0_1043
	s_waitcnt lgkmcnt(0)
	v_mov_b32_e32 v232, 0x1000
	global_load_dword v216, v129, s[6:7] offset:1024 sc1
	global_load_dword v217, v129, s[6:7] offset:1280 sc1
	global_load_dword v218, v129, s[6:7] offset:1536 sc1
	global_load_dword v219, v129, s[6:7] offset:1792 sc1
	global_load_dword v220, v129, s[6:7] offset:2048 sc1
	global_load_dword v221, v129, s[6:7] offset:2304 sc1
	global_load_dword v222, v129, s[6:7] offset:2560 sc1
	global_load_dword v223, v129, s[6:7] offset:2816 sc1
	global_load_dword v224, v129, s[6:7] offset:3072 sc1
	global_load_dword v225, v129, s[6:7] offset:3328 sc1
	global_load_dword v226, v129, s[6:7] offset:3584 sc1
	global_load_dword v227, v129, s[6:7] offset:3840 sc1
	global_load_dword v228, v232, s[6:7] sc1
	global_load_dword v229, v232, s[6:7] offset:256 sc1
	global_load_dword v230, v232, s[6:7] offset:512 sc1
	global_load_dword v231, v232, s[6:7] offset:768 sc1
	v_mov_b32_e32 v0, -1
	s_waitcnt vmcnt(0)
	v_cmp_ne_u32_e32 vcc, 32, v216
	s_cbranch_vccnz .LBB0_1043
	v_mov_b32_e32 v0, -1
	s_waitcnt vmcnt(0)
	v_cmp_ne_u32_e32 vcc, 32, v217
	s_cbranch_vccnz .LBB0_1043
	v_mov_b32_e32 v0, -1
	s_waitcnt vmcnt(0)
	v_cmp_ne_u32_e32 vcc, 32, v218
	s_cbranch_vccnz .LBB0_1043
	v_mov_b32_e32 v0, -1
	s_waitcnt vmcnt(0)
	v_cmp_ne_u32_e32 vcc, 32, v219
	s_cbranch_vccnz .LBB0_1043
	v_mov_b32_e32 v0, -1
	s_waitcnt vmcnt(0)
	v_cmp_ne_u32_e32 vcc, 32, v220
	s_cbranch_vccnz .LBB0_1043
	v_mov_b32_e32 v0, -1
	s_waitcnt vmcnt(0)
	v_cmp_ne_u32_e32 vcc, 32, v221
	s_cbranch_vccnz .LBB0_1043
	v_mov_b32_e32 v0, -1
	s_waitcnt vmcnt(0)
	v_cmp_ne_u32_e32 vcc, 32, v222
	s_cbranch_vccnz .LBB0_1043
	v_mov_b32_e32 v0, -1
	s_waitcnt vmcnt(0)
	v_cmp_ne_u32_e32 vcc, 32, v223
	s_cbranch_vccnz .LBB0_1043
	v_mov_b32_e32 v0, -1
	s_waitcnt vmcnt(0)
	v_cmp_ne_u32_e32 vcc, 0, v224
	s_cbranch_vccnz .LBB0_1043
	v_mov_b32_e32 v0, -1
	s_waitcnt vmcnt(0)
	v_cmp_ne_u32_e32 vcc, 0, v225
	s_cbranch_vccnz .LBB0_1043
	v_mov_b32_e32 v0, -1
	s_waitcnt vmcnt(0)
	v_cmp_ne_u32_e32 vcc, 0, v226
	s_cbranch_vccnz .LBB0_1043
	v_mov_b32_e32 v0, -1
	s_waitcnt vmcnt(0)
	v_cmp_ne_u32_e32 vcc, 0, v227
	s_cbranch_vccnz .LBB0_1043
	v_mov_b32_e32 v0, -1
	s_waitcnt vmcnt(0)
	v_cmp_ne_u32_e32 vcc, 0, v228
	s_cbranch_vccnz .LBB0_1043
	v_mov_b32_e32 v0, -1
	s_waitcnt vmcnt(0)
	v_cmp_ne_u32_e32 vcc, 0, v229
	s_cbranch_vccnz .LBB0_1043
	v_mov_b32_e32 v0, -1
	s_waitcnt vmcnt(0)
	v_cmp_ne_u32_e32 vcc, 0, v230
	s_cbranch_vccnz .LBB0_1043
	v_mov_b32_e32 v0, -1
	s_waitcnt vmcnt(0)
	v_cmp_ne_u32_e32 vcc, 0, v231
	s_cbranch_vccnz .LBB0_1042
	s_mov_b64 s[10:11], exec
	v_mbcnt_lo_u32_b32 v0, s10, 0
	s_getreg_b32 s0, hwreg(HW_REG_XCC_ID, 0, 4)
	v_mbcnt_hi_u32_b32 v0, s11, v0
	s_and_b32 s0, s0, 15
	v_cmp_eq_u32_e32 vcc, 0, v0
	s_and_saveexec_b64 s[12:13], vcc
	s_cbranch_execz .LBB0_1041
	v_readlane_b32 s1, v255, 0
	s_lshl_b32 s1, s1, 4
	s_or_b32 s38, s0, s1
	s_lshl_b64 s[14:15], s[38:39], 2
	s_add_u32 s14, s6, s14
	s_addc_u32 s15, s7, s15
	s_bcnt1_i32_b64 s1, s[10:11]
	v_mov_b32_e32 v1, s1
	v_mov_b32_e32 v2, 0x8000
	global_atomic_add v1, v2, v1, s[14:15] sc0
